# convert_layer_weights: LDS-reuse barrier moved from the loop latch to just before the LDS writes so the next tile loads issue earlier (on top of v41)
# speedup vs baseline: 1.0022x; 1.0018x over previous
; #define p (kparams())
; #define ws (kparams()->ws)
; __device__ __forceinline__ void conv_tile(const int wv_, const WDesc w, const int ti, float* tile  ) {
;     ...
;       bf16_t* dp = w.dst + (size_t)row * w.K + k0 + ks;
;       *(u32x4*)dp = a; *(u32x4*)(dp + 8) = b; } }
;   __syncthreads();
; }
; __device__ __forceinline__ void convert_layer_weights(const int wv_, KPR p, int l, float* tile) {
;   unsigned char* ws = p->ws;
;   constexpr int T_WIN = 3840, T_WBR = T_WIN + 512, T_WOUT = T_WBR + 512, T_W1 = T_WOUT + 2048, T_W2 = T_W1 + 2048, T_RW2 = T_W2 + 8, T_RA2 = T_RW2 + 8, T_ALL = T_RA2 + 8;
;   for (int g = blockIdx.x; g < T_ALL; g += gridDim.x) {
.LBB0_87:
	s_or_b64 exec, exec, s[34:35]
	s_add_i32 s51, s51, s33
	s_cmpk_lt_i32 s51, 0x2318
	s_cbranch_scc0 .LBB0_127

; __device__ __forceinline__ unsigned pk2(float lo, float hi) { f32x2n v = {lo, hi}; bf16x2n b = __builtin_convertvector(v, bf16x2n); return __builtin_bit_cast(unsigned, b); }
; __device__ __forceinline__ void conv_tile(const int wv_, const WDesc w, const int ti, float* tile  ) {
;     ...
;   for (int i = 0; i < 4; ++i) { const int idx = tid + 512 * i, k = idx >> 5, n4 = (idx & 31) * 4;
;     f32x4 v = (f32x4){0.f, 0.f, 0.f, 0.f};
;     if (n0 + n4 < w.N) v = *(const f32x4*)(w.src + (size_t)(k0 + k) * w.N + n0 + n4);
;     float* tp = tile + k * 129 + n4; tp[0] = v[0]; tp[1] = v[1]; tp[2] = v[2]; tp[3] = v[3]; }
;   __syncthreads();
;   { const int n = tid >> 2, ks = (tid & 3) * 16, ng = n0 + n;
;     if (ng < w.N) { const int row = ng < w.gap_at ? ng : ng + w.gap;
;       const float* tp = tile + ks * 129 + n;
;       u32x4 a, b;
;       a.x = pk2(tp[0 * 129], tp[1 * 129]); a.y = pk2(tp[2 * 129], tp[3 * 129]); a.z = pk2(tp[4 * 129], tp[5 * 129]); a.w = pk2(tp[6 * 129], tp[7 * 129]);
;       b.x = pk2(tp[8 * 129], tp[9 * 129]); b.y = pk2(tp[10 * 129], tp[11 * 129]); b.z = pk2(tp[12 * 129], tp[13 * 129]); b.w = pk2(tp[14 * 129], tp[15 * 129]);
;       bf16_t* dp = w.dst + (size_t)row * w.K + k0 + ks;
;       *(u32x4*)dp = a; *(u32x4*)(dp + 8) = b; } }
;   __syncthreads();
.Lcv_noload:
	s_or_b64 exec, exec, s[34:35]
	s_barrier
	v_mad_u64_u32 v[108:109], s[34:35], v104, s76, v[10:11]
	v_mad_u64_u32 v[110:111], s[34:35], v105, s76, v[10:11]
	v_mad_u64_u32 v[112:113], s[34:35], v106, s76, v[10:11]
	v_mad_u64_u32 v[12:13], s[34:35], v12, s76, v[10:11]
	v_ashrrev_i32_e32 v1, 2, v11
	s_waitcnt vmcnt(3)
	ds_write2_b32 v12, v88, v89 offset1:1
	ds_write2_b32 v12, v90, v91 offset0:2 offset1:3
	s_waitcnt vmcnt(2)
	ds_write2_b32 v108, v92, v93 offset1:1
	ds_write2_b32 v108, v94, v95 offset0:2 offset1:3
	s_waitcnt vmcnt(1)
	ds_write2_b32 v110, v96, v97 offset1:1
	ds_write2_b32 v110, v98, v99 offset0:2 offset1:3
	s_waitcnt vmcnt(0)
	ds_write2_b32 v112, v100, v101 offset1:1
	ds_write2_b32 v112, v102, v103 offset0:2 offset1:3
	v_add_u32_e32 v0, s38, v1
	v_cmp_gt_i32_e32 vcc, s53, v0
	s_waitcnt lgkmcnt(0)
	s_barrier
	s_and_saveexec_b64 s[34:35], vcc
	s_cbranch_execz .LBB0_87
	v_lshlrev_b32_e32 v3, 4, v3
	v_and_b32_e32 v3, 48, v3
	v_mul_u32_u24_e32 v4, 0x204, v3
	v_lshlrev_b32_e32 v1, 2, v1
	v_add3_u32 v14, 0, v4, v1
	v_add_u32_e32 v1, 0x400, v14
	ds_read2_b32 v[4:5], v14 offset1:129
	ds_read2_b32 v[6:7], v1 offset0:2 offset1:131
	v_add_u32_e32 v1, 0x800, v14
	ds_read2_b32 v[8:9], v1 offset0:4 offset1:133
	v_mov_b32_e32 v10, s56
	v_cmp_le_i32_e32 vcc, s37, v0
	s_waitcnt lgkmcnt(2)
	v_cvt_pk_bf16_f32 v4, v4, v5
	s_waitcnt lgkmcnt(1)
	v_cvt_pk_bf16_f32 v5, v6, v7
	v_cndmask_b32_e32 v1, 0, v10, vcc
	v_add_u32_e32 v7, 0x1000, v14
	v_add_u32_e32 v16, v1, v0
	s_waitcnt lgkmcnt(0)
	v_cvt_pk_bf16_f32 v6, v8, v9
	v_add_u32_e32 v0, 0xc00, v14
	ds_read2_b32 v[8:9], v7 offset0:8 offset1:137
	v_add_u32_e32 v7, 0x1400, v14
	ds_read2_b32 v[0:1], v0 offset0:6 offset1:135
	ds_read2_b32 v[10:11], v7 offset0:10 offset1:139
	v_add_u32_e32 v7, 0x1800, v14
	ds_read2_b32 v[12:13], v7 offset0:12 offset1:141
	v_add_u32_e32 v7, 0x1c00, v14
	ds_read2_b32 v[14:15], v7 offset0:14 offset1:143
	s_waitcnt lgkmcnt(3)
	v_cvt_pk_bf16_f32 v7, v0, v1
	v_ashrrev_i32_e32 v0, 31, v16
	v_cvt_pk_bf16_f32 v8, v8, v9
	s_waitcnt lgkmcnt(2)
	v_cvt_pk_bf16_f32 v9, v10, v11
	s_waitcnt lgkmcnt(1)
	v_cvt_pk_bf16_f32 v10, v12, v13
	v_mul_lo_u32 v12, s28, v0
	v_mul_lo_u32 v13, s29, v16
	v_mad_u64_u32 v[0:1], s[28:29], s28, v16, 0
	v_add3_u32 v1, v1, v12, v13
	v_lshl_add_u64 v[0:1], v[0:1], 1, s[30:31]
	s_ashr_i32 s37, s36, 31
	v_lshl_add_u64 v[0:1], s[36:37], 1, v[0:1]
	v_lshlrev_b32_e32 v12, 1, v3
	v_mov_b32_e32 v13, v2
	v_lshl_add_u64 v[0:1], v[0:1], 0, v[12:13]
	s_waitcnt lgkmcnt(0)
	v_cvt_pk_bf16_f32 v11, v14, v15
	global_store_dwordx4 v[0:1], v[4:7], off
	global_store_dwordx4 v[0:1], v[8:11], off offset:16
	s_branch .LBB0_87
.LBB0_127:
	s_barrier
	s_movk_i32 s35, 0x43ff
	s_movk_i32 s31, 0xd80
	s_movk_i32 s34, 0xffc0
	s_movk_i32 s36, 0x3080
	s_mov_b32 s37, 0x3f317217
	s_mov_b32 s38, 0x7f800000
